# attention sample-unit producer: K/V cache base pointers fetched together one step early, third tile's row loads issue back to back (was one round trip per pass); on top of MFMA-head trim + barrier XGE
# baseline (speedup 1.0000x reference)
; #define LAS __attribute__((address_space(3)))
; __device__ __forceinline__ unsigned pk2(float lo, float hi) { const f32x2 v = {lo, hi}; return __builtin_bit_cast(unsigned, __builtin_convertvector(v, bf16x2_t)); }
; template <bool SAMP>
; __device__ __forceinline__ void attn_unit2(const Args& a, LAS unsigned char* lds, int n, int cch, int h) {
;     ...
;         auto tile_load = [&](int kc) {
;             if (SAMP && kc < 8) {
; #pragma unroll
;                 for (int p = 0; p < 8; ++p) { const int r = prow + 16 * p, kv = r >> 6, key = r & 63;
;                     const float* src = a.in[kv ? 5 : 4] + (((size_t)n * 512 + (size_t)kc * 64 + key) * NH + h) * HD + 8 * scc; R[2 * p] = *(const f32x4*)src; R[2 * p + 1] = *(const f32x4*)(src + 4); }
;             } else {
;     ...
;         auto tile_store = [&](int kc, int buf) {
;             LAS unsigned char* bb = lds + buf * AT2_BUF;
; #pragma unroll
;             for (int p = 0; p < 8; ++p) { const int r = prow + 16 * p, kv = r >> 6, key = r & 63; u32x4 w;
;                 if (SAMP && kc < 8) { const f32x4 x0 = R[2 * p], x1 = R[2 * p + 1]; w.x = pk2(x0[0], x0[1]); w.y = pk2(x0[2], x0[3]); w.z = pk2(x1[0], x1[1]); w.w = pk2(x1[2], x1[3]); }
;                 else w = __builtin_bit_cast(u32x4, R[p]);
;                 *(LAS u32x4*)(bb + (kv ? AT_TILE + (key * AT_VS + 8 * scc) * 2 : (key * AT_KS + 8 * scc) * 2)) = w; }
;     ...
;         tile_load(k0); tile_store(k0, 0);
.LBB0_823:
	s_or_b64 exec, exec, s[2:3]
	v_ashrrev_i32_e32 v109, 4, v2
	v_mov_b32_e32 v2, s79
	v_mov_b32_e32 v3, s76
	v_cmp_gt_u32_e32 vcc, 64, v109
	v_mov_b32_e32 v4, s77
	v_mov_b32_e32 v5, s75
	v_add_u32_e32 v117, 16, v109
	v_add_u32_e32 v116, 32, v109
	v_add_u32_e32 v113, 48, v109
	v_cmp_lt_u32_e64 s[12:13], s91, v109
	v_cndmask_b32_e32 v75, v2, v3, vcc
	v_cndmask_b32_e32 v74, v4, v5, vcc
	v_cmp_gt_u32_e64 s[8:9], 64, v117
	v_cmp_gt_u32_e64 s[10:11], 64, v116
	v_cndmask_b32_e64 v83, v2, v3, s[12:13]
	v_cndmask_b32_e64 v82, v4, v5, s[12:13]
	v_cmp_gt_u32_e64 s[16:17], 64, v113
	global_load_dwordx2 v[66:67], v[74:75], off
	v_cndmask_b32_e64 v77, v2, v3, s[8:9]
	v_cndmask_b32_e64 v76, v4, v5, s[8:9]
	v_cndmask_b32_e64 v79, v2, v3, s[10:11]
	v_cndmask_b32_e64 v78, v4, v5, s[10:11]
	global_load_dwordx2 v[72:73], v[82:83], off
	v_cndmask_b32_e64 v81, v2, v3, s[16:17]
	v_cndmask_b32_e64 v80, v4, v5, s[16:17]
	global_load_dwordx2 v[68:69], v[76:77], off
	global_load_dwordx2 v[70:71], v[78:79], off
	global_load_dwordx2 v[92:93], v[80:81], off
	v_add_u32_e32 v112, 0x50, v109
	v_cmp_gt_u32_e64 s[14:15], 64, v112
	v_add_u32_e32 v111, 0x60, v109
	v_add_u32_e32 v110, 0x70, v109
	v_cndmask_b32_e64 v85, v2, v3, s[14:15]
	v_cndmask_b32_e64 v84, v4, v5, s[14:15]
	global_load_dwordx2 v[90:91], v[84:85], off
	v_cmp_gt_u32_e64 s[18:19], 64, v111
	v_cmp_gt_u32_e64 s[20:21], 64, v110
	s_mov_b32 s57, s40
	v_cndmask_b32_e64 v87, v2, v3, s[18:19]
	v_cndmask_b32_e64 v86, v4, v5, s[18:19]
	v_cndmask_b32_e64 v89, v2, v3, s[20:21]
	v_cndmask_b32_e64 v88, v4, v5, s[20:21]
	global_load_dwordx2 v[94:95], v[86:87], off
	global_load_dwordx2 v[96:97], v[88:89], off
	v_and_b32_e32 v108, 63, v109
	s_lshl_b64 s[42:43], s[56:57], 9
	v_or_b32_e32 v2, s42, v108
	v_mov_b32_e32 v3, s43
	v_and_b32_e32 v107, 63, v117
	v_and_b32_e32 v104, 63, v116
	v_lshlrev_b64 v[4:5], 13, v[2:3]
	v_or_b32_e32 v2, s42, v107
	v_and_b32_e32 v103, 63, v113
	s_waitcnt vmcnt(15)
	v_lshlrev_b64 v[6:7], 13, v[2:3]
	v_or_b32_e32 v2, s42, v104
	v_lshlrev_b64 v[8:9], 13, v[2:3]
	v_or_b32_e32 v2, s42, v103
	s_lshl_b32 s2, s97, 9
	s_mov_b32 s3, s40
	s_waitcnt vmcnt(14)
	v_lshlrev_b64 v[10:11], 13, v[2:3]
	v_lshlrev_b32_e32 v114, 5, v99
	v_and_b32_e32 v102, 63, v112
	v_or_b32_e32 v2, s42, v102
	v_and_b32_e32 v106, 63, v111
	v_and_b32_e32 v105, 63, v110
	v_cmp_lt_u32_e64 s[36:37], 63, v109
	v_cmp_lt_u32_e64 s[34:35], 63, v117
	v_cmp_lt_u32_e64 s[30:31], 63, v116
	v_cmp_lt_u32_e64 s[28:29], 63, v113
	v_cmp_gt_u32_e64 s[26:27], s90, v109
	v_cmp_lt_u32_e64 s[24:25], 63, v112
	v_cmp_lt_u32_e64 s[22:23], 63, v111
	v_cmp_lt_u32_e64 s[20:21], 63, v110
	v_lshlrev_b32_e32 v98, 4, v99
	s_waitcnt vmcnt(7)
	v_lshl_add_u64 v[12:13], v[66:67], 0, v[4:5]
	v_lshl_add_u64 v[12:13], v[12:13], 0, s[2:3]
	v_lshl_add_u64 v[12:13], v[12:13], 0, v[114:115]
	global_load_dwordx4 v[58:61], v[12:13], off offset:16
	global_load_dwordx4 v[62:65], v[12:13], off
	s_waitcnt vmcnt(8)
	v_lshl_add_u64 v[4:5], v[72:73], 0, v[4:5]
	v_lshl_add_u64 v[4:5], v[4:5], 0, s[2:3]
	v_lshl_add_u64 v[4:5], v[4:5], 0, v[114:115]
	s_waitcnt vmcnt(7)
	v_lshl_add_u64 v[6:7], v[68:69], 0, v[6:7]
	s_waitcnt vmcnt(6)
	v_lshl_add_u64 v[8:9], v[70:71], 0, v[8:9]
	s_waitcnt vmcnt(5)
	v_lshl_add_u64 v[10:11], v[92:93], 0, v[10:11]
	v_lshl_add_u64 v[6:7], v[6:7], 0, s[2:3]
	v_lshl_add_u64 v[8:9], v[8:9], 0, s[2:3]
	v_lshl_add_u64 v[10:11], v[10:11], 0, s[2:3]
	v_lshl_add_u64 v[6:7], v[6:7], 0, v[114:115]
	v_lshl_add_u64 v[8:9], v[8:9], 0, v[114:115]
	v_lshl_add_u64 v[10:11], v[10:11], 0, v[114:115]
	global_load_dwordx4 v[26:29], v[4:5], off offset:16
	global_load_dwordx4 v[30:33], v[4:5], off
	global_load_dwordx4 v[50:53], v[6:7], off offset:16
	global_load_dwordx4 v[54:57], v[6:7], off
	global_load_dwordx4 v[42:45], v[8:9], off offset:16
	global_load_dwordx4 v[46:49], v[8:9], off
	global_load_dwordx4 v[34:37], v[10:11], off offset:16
	global_load_dwordx4 v[38:41], v[10:11], off
	v_lshlrev_b64 v[4:5], 13, v[2:3]
	s_waitcnt vmcnt(12)
	v_lshl_add_u64 v[4:5], v[90:91], 0, v[4:5]
	v_lshl_add_u64 v[4:5], v[4:5], 0, s[2:3]
	v_lshl_add_u64 v[4:5], v[4:5], 0, v[114:115]
	v_or_b32_e32 v2, s42, v106
	global_load_dwordx4 v[18:21], v[4:5], off offset:16
	global_load_dwordx4 v[22:25], v[4:5], off
	v_lshlrev_b64 v[4:5], 13, v[2:3]
	v_or_b32_e32 v2, s42, v105
	v_lshlrev_b64 v[2:3], 13, v[2:3]
	s_waitcnt vmcnt(13)
	v_lshl_add_u64 v[4:5], v[94:95], 0, v[4:5]
	s_waitcnt vmcnt(12)
	v_lshl_add_u64 v[2:3], v[96:97], 0, v[2:3]
	v_lshl_add_u64 v[4:5], v[4:5], 0, s[2:3]
	v_lshl_add_u64 v[2:3], v[2:3], 0, s[2:3]
	v_lshl_add_u64 v[4:5], v[4:5], 0, v[114:115]
	v_lshl_add_u64 v[6:7], v[2:3], 0, v[114:115]
	global_load_dwordx4 v[10:13], v[4:5], off offset:16
	global_load_dwordx4 v[14:17], v[4:5], off
	s_nop 0
	global_load_dwordx4 v[2:5], v[6:7], off offset:16
	s_nop 0
	global_load_dwordx4 v[6:9], v[6:7], off
	v_mul_u32_u24_e32 v114, 0x120, v108
	s_and_saveexec_b64 s[4:5], s[36:37]
	s_xor_b64 s[4:5], exec, s[4:5]
	v_mul_u32_u24_e32 v100, 0x120, v108
	v_add3_u32 v100, v100, v98, s93
	s_andn2_saveexec_b64 s[4:5], s[4:5]
	v_mad_u64_u32 v[100:101], s[36:37], v109, s85, v[98:99]
	s_or_b64 exec, exec, s[4:5]
	s_waitcnt vmcnt(14)
	v_cvt_pk_bf16_f32 v62, v62, v63
	v_cvt_pk_bf16_f32 v63, v64, v65
	v_cvt_pk_bf16_f32 v64, v58, v59
	v_cvt_pk_bf16_f32 v65, v60, v61
	v_add_u32_e32 v58, 0, v100
	ds_write_b128 v58, v[62:65]
	s_and_saveexec_b64 s[4:5], s[34:35]
	s_xor_b64 s[4:5], exec, s[4:5]
	v_mul_u32_u24_e32 v58, 0x120, v107
	v_add3_u32 v58, v58, v98, s93
	s_andn2_saveexec_b64 s[4:5], s[4:5]
	v_mad_u64_u32 v[58:59], s[34:35], v117, s85, v[98:99]
	s_or_b64 exec, exec, s[4:5]
	s_waitcnt vmcnt(10)
; #define LAS __attribute__((address_space(3)))
; __device__ __forceinline__ unsigned pk2(float lo, float hi) { const f32x2 v = {lo, hi}; return __builtin_bit_cast(unsigned, __builtin_convertvector(v, bf16x2_t)); }
; template <bool SAMP>
; __device__ __forceinline__ void attn_unit2(const Args& a, LAS unsigned char* lds, int n, int cch, int h) {
;     ...
;         auto tile_store = [&](int kc, int buf) {
;             LAS unsigned char* bb = lds + buf * AT2_BUF;
; #pragma unroll
;             for (int p = 0; p < 8; ++p) { const int r = prow + 16 * p, kv = r >> 6, key = r & 63; u32x4 w;
;                 if (SAMP && kc < 8) { const f32x4 x0 = R[2 * p], x1 = R[2 * p + 1]; w.x = pk2(x0[0], x0[1]); w.y = pk2(x0[2], x0[3]); w.z = pk2(x1[0], x1[1]); w.w = pk2(x1[2], x1[3]); }
;                 else w = __builtin_bit_cast(u32x4, R[p]);
;                 *(LAS u32x4*)(bb + (kv ? AT_TILE + (key * AT_VS + 8 * scc) * 2 : (key * AT_KS + 8 * scc) * 2)) = w; }
;     ...
;         if (k0 < k1) tile_load(k0 + 1);
;         __syncthreads();
	v_cvt_pk_bf16_f32 v54, v54, v55
	v_cvt_pk_bf16_f32 v55, v56, v57
	v_cvt_pk_bf16_f32 v56, v50, v51
	v_cvt_pk_bf16_f32 v57, v52, v53
	v_add_u32_e32 v50, 0, v58
	ds_write_b128 v50, v[54:57]
	s_and_saveexec_b64 s[4:5], s[30:31]
	s_xor_b64 s[4:5], exec, s[4:5]
	v_mul_u32_u24_e32 v50, 0x120, v104
	v_add3_u32 v50, v50, v98, s93
	s_andn2_saveexec_b64 s[4:5], s[4:5]
	v_mad_u64_u32 v[50:51], s[30:31], v116, s85, v[98:99]
	s_or_b64 exec, exec, s[4:5]
	s_waitcnt vmcnt(8)
	v_cvt_pk_bf16_f32 v46, v46, v47
	v_cvt_pk_bf16_f32 v47, v48, v49
	v_cvt_pk_bf16_f32 v48, v42, v43
	v_cvt_pk_bf16_f32 v49, v44, v45
	v_add_u32_e32 v42, 0, v50
	ds_write_b128 v42, v[46:49]
	s_and_saveexec_b64 s[4:5], s[28:29]
	s_xor_b64 s[4:5], exec, s[4:5]
	v_mul_u32_u24_e32 v42, 0x120, v103
	v_add3_u32 v42, v42, v98, s93
	s_andn2_saveexec_b64 s[4:5], s[4:5]
	v_mad_u64_u32 v[42:43], s[28:29], v113, s85, v[98:99]
	s_or_b64 exec, exec, s[4:5]
	s_waitcnt vmcnt(6)
	v_cvt_pk_bf16_f32 v38, v38, v39
	v_cvt_pk_bf16_f32 v39, v40, v41
	v_cvt_pk_bf16_f32 v40, v34, v35
	v_cvt_pk_bf16_f32 v41, v36, v37
	v_add_u32_e32 v34, 0, v42
	ds_write_b128 v34, v[38:41]
	s_and_saveexec_b64 s[4:5], s[26:27]
	s_xor_b64 s[4:5], exec, s[4:5]
	s_or_saveexec_b64 s[4:5], s[4:5]
	v_mul_lo_u32 v34, v109, s85
	s_xor_b64 exec, exec, s[4:5]
	v_mov_b32_e32 v114, v34
	s_or_b64 exec, exec, s[4:5]
	v_cvt_pk_bf16_f32 v30, v30, v31
	v_cvt_pk_bf16_f32 v31, v32, v33
	v_cvt_pk_bf16_f32 v32, v26, v27
	v_cvt_pk_bf16_f32 v33, v28, v29
	v_add3_u32 v26, 0, v98, v114
	ds_write_b128 v26, v[30:33] offset:17408
	s_and_saveexec_b64 s[4:5], s[24:25]
	s_xor_b64 s[4:5], exec, s[4:5]
	v_mul_u32_u24_e32 v26, 0x120, v102
	v_add3_u32 v26, v26, v98, s93
	s_andn2_saveexec_b64 s[4:5], s[4:5]
	v_mad_u64_u32 v[26:27], s[24:25], v112, s85, v[98:99]
	s_or_b64 exec, exec, s[4:5]
	s_waitcnt vmcnt(4)
	v_cvt_pk_bf16_f32 v22, v22, v23
	v_cvt_pk_bf16_f32 v23, v24, v25
	v_cvt_pk_bf16_f32 v24, v18, v19
	v_cvt_pk_bf16_f32 v25, v20, v21
	v_add_u32_e32 v18, 0, v26
	ds_write_b128 v18, v[22:25]
	s_and_saveexec_b64 s[4:5], s[22:23]
	s_xor_b64 s[4:5], exec, s[4:5]
	v_mul_u32_u24_e32 v18, 0x120, v106
	v_add3_u32 v18, v18, v98, s93
	s_andn2_saveexec_b64 s[4:5], s[4:5]
	v_mad_u64_u32 v[18:19], s[22:23], v111, s85, v[98:99]
	s_or_b64 exec, exec, s[4:5]
	s_waitcnt vmcnt(2)
	v_cvt_pk_bf16_f32 v14, v14, v15
	v_cvt_pk_bf16_f32 v15, v16, v17
	v_cvt_pk_bf16_f32 v16, v10, v11
	v_cvt_pk_bf16_f32 v17, v12, v13
	v_add_u32_e32 v10, 0, v18
	ds_write_b128 v10, v[14:17]
	v_or_b32_e32 v14, 0x4400, v98
	s_and_saveexec_b64 s[4:5], s[20:21]
	s_xor_b64 s[4:5], exec, s[4:5]
	v_or_b32_e32 v14, 0x4400, v98
	v_mad_u32_u24 v10, v105, s92, v14
	s_or_saveexec_b64 s[4:5], s[4:5]
	v_mov_b64_e32 v[12:13], 0x28100000
	s_xor_b64 exec, exec, s[4:5]
	v_mad_u64_u32 v[10:11], s[20:21], v110, s85, v[98:99]
	v_mov_b64_e32 v[12:13], 0x25900000
	s_or_b64 exec, exec, s[4:5]
	s_or_b32 s4, s42, 64
	s_waitcnt vmcnt(0)
	v_cvt_pk_bf16_f32 v6, v6, v7
	v_cvt_pk_bf16_f32 v7, v8, v9
	v_cvt_pk_bf16_f32 v8, v2, v3
	v_mov_b32_e32 v3, s43
	v_or_b32_e32 v2, s4, v108
	v_lshlrev_b64 v[40:41], 13, v[2:3]
	v_lshlrev_b32_e32 v58, 3, v99
	v_lshl_add_u64 v[2:3], v[66:67], 0, v[40:41]
	v_cvt_pk_bf16_f32 v9, v4, v5
	v_add_u32_e32 v99, 0, v10
	v_lshl_add_u64 v[2:3], v[2:3], 0, s[2:3]
	v_lshlrev_b32_e32 v114, 2, v58
	v_mov_b32_e32 v11, s43
	v_or_b32_e32 v10, s4, v107
	ds_write_b128 v99, v[6:9]
	v_lshl_add_u64 v[6:7], v[2:3], 0, v[114:115]
	v_lshlrev_b64 v[10:11], 13, v[10:11]
	v_mov_b32_e32 v21, s43
	v_or_b32_e32 v20, s4, v104
	v_mov_b32_e32 v29, s43
	v_or_b32_e32 v28, s4, v103
	v_mov_b32_e32 v49, s43
	v_or_b32_e32 v48, s4, v102
	v_mov_b32_e32 v57, s43
	v_or_b32_e32 v56, s4, v106
	global_load_dwordx4 v[2:5], v[6:7], off offset:16
	s_nop 0
	global_load_dwordx4 v[6:9], v[6:7], off
	v_lshl_add_u64 v[10:11], v[68:69], 0, v[10:11]
	v_lshlrev_b64 v[20:21], 13, v[20:21]
	v_lshlrev_b64 v[28:29], 13, v[28:29]
	v_lshlrev_b64 v[48:49], 13, v[48:49]
	v_lshlrev_b64 v[56:57], 13, v[56:57]
	v_lshl_add_u64 v[10:11], v[10:11], 0, s[2:3]
	v_lshl_add_u64 v[20:21], v[70:71], 0, v[20:21]
	v_lshl_add_u64 v[28:29], v[92:93], 0, v[28:29]
	v_lshl_add_u64 v[40:41], v[72:73], 0, v[40:41]
	v_lshl_add_u64 v[48:49], v[90:91], 0, v[48:49]
	v_lshl_add_u64 v[56:57], v[94:95], 0, v[56:57]
	v_lshl_add_u64 v[16:17], v[10:11], 0, v[114:115]
	v_lshl_add_u64 v[20:21], v[20:21], 0, s[2:3]
	v_lshl_add_u64 v[28:29], v[28:29], 0, s[2:3]
	v_lshl_add_u64 v[40:41], v[40:41], 0, s[2:3]
	v_lshl_add_u64 v[48:49], v[48:49], 0, s[2:3]
	v_lshl_add_u64 v[56:57], v[56:57], 0, s[2:3]
	v_lshl_add_u64 v[32:33], s[68:69], 0, v[12:13]
	global_load_dwordx4 v[10:13], v[16:17], off offset:16
	s_nop 0
	global_load_dwordx4 v[16:19], v[16:17], off
	v_lshl_add_u64 v[24:25], v[20:21], 0, v[114:115]
	v_lshl_add_u64 v[36:37], v[28:29], 0, v[114:115]
	v_lshl_add_u64 v[44:45], v[40:41], 0, v[114:115]
	v_lshl_add_u64 v[52:53], v[48:49], 0, v[114:115]
	v_lshl_add_u64 v[56:57], v[56:57], 0, v[114:115]
	global_load_dwordx4 v[20:23], v[24:25], off offset:16
	s_nop 0
	global_load_dwordx4 v[24:27], v[24:25], off
	s_nop 0
	global_load_dwordx4 v[28:31], v[36:37], off offset:16
	s_nop 0
	global_load_dwordx4 v[36:39], v[36:37], off
	s_nop 0
	global_load_dwordx4 v[40:43], v[44:45], off offset:16
	s_nop 0
	global_load_dwordx4 v[44:47], v[44:45], off
	s_nop 0
	global_load_dwordx4 v[48:51], v[52:53], off offset:16
	s_nop 0
	global_load_dwordx4 v[52:55], v[52:53], off
	s_nop 0
	global_load_dwordx4 v[110:113], v[56:57], off offset:16
	global_load_dwordx4 v[116:119], v[56:57], off
	v_mov_b32_e32 v57, s43
	v_or_b32_e32 v56, s4, v105
	v_lshlrev_b64 v[56:57], 13, v[56:57]
	v_lshl_add_u64 v[56:57], v[96:97], 0, v[56:57]
	v_lshl_add_u64 v[56:57], v[56:57], 0, s[2:3]
	v_lshl_add_u64 v[56:57], v[56:57], 0, v[114:115]
	global_load_dwordx4 v[122:125], v[56:57], off offset:16
	global_load_dwordx4 v[126:129], v[56:57], off
	s_waitcnt lgkmcnt(0)
	s_barrier
; #define LAS __attribute__((address_space(3)))
; __device__ __forceinline__ unsigned pk2(float lo, float hi) { const f32x2 v = {lo, hi}; return __builtin_bit_cast(unsigned, __builtin_convertvector(v, bf16x2_t)); }
; template <bool SAMP>
; __device__ __forceinline__ void attn_unit2(const Args& a, LAS unsigned char* lds, int n, int cch, int h) {
;     ...
;         auto tile_load = [&](int kc) {
;             if (SAMP && kc < 8) {
; #pragma unroll
;                 for (int p = 0; p < 8; ++p) { const int r = prow + 16 * p, kv = r >> 6, key = r & 63;
;                     const float* src = a.in[kv ? 5 : 4] + (((size_t)n * 512 + (size_t)kc * 64 + key) * NH + h) * HD + 8 * scc; R[2 * p] = *(const f32x4*)src; R[2 * p + 1] = *(const f32x4*)(src + 4); }
;             } else {
;     ...
;         auto tile_store = [&](int kc, int buf) {
;             LAS unsigned char* bb = lds + buf * AT2_BUF;
; #pragma unroll
;             for (int p = 0; p < 8; ++p) { const int r = prow + 16 * p, kv = r >> 6, key = r & 63; u32x4 w;
;                 if (SAMP && kc < 8) { const f32x4 x0 = R[2 * p], x1 = R[2 * p + 1]; w.x = pk2(x0[0], x0[1]); w.y = pk2(x0[2], x0[3]); w.z = pk2(x1[0], x1[1]); w.w = pk2(x1[2], x1[3]); }
;                 else w = __builtin_bit_cast(u32x4, R[p]);
;                 *(LAS u32x4*)(bb + (kv ? AT_TILE + (key * AT_VS + 8 * scc) * 2 : (key * AT_KS + 8 * scc) * 2)) = w; }
;     ...
;         for (int kc = k0; kc <= k1; ++kc) {
;             if (kc < k1) { tile_store(kc + 1, (kc - k0 + 1) & 1); if (kc + 1 < k1) tile_load(kc + 2); }
	global_load_dwordx2 v[74:75], v[74:75], off
	global_load_dwordx2 v[76:77], v[76:77], off
	global_load_dwordx2 v[78:79], v[78:79], off
	global_load_dwordx2 v[80:81], v[80:81], off
	global_load_dwordx2 v[82:83], v[82:83], off
	global_load_dwordx2 v[84:85], v[84:85], off
	global_load_dwordx2 v[86:87], v[86:87], off
	global_load_dwordx2 v[88:89], v[88:89], off
	s_lshl_b64 s[4:5], s[56:57], 6
	s_add_u32 s20, s4, 0x2000
	s_addc_u32 s21, s5, 0
	v_mad_u32_u24 v94, v108, s92, v14
	v_add_u32_e32 v90, v34, v98
	v_mad_u32_u24 v91, v107, s92, v14
	v_mad_u32_u24 v93, v104, s92, v14
	v_mad_u32_u24 v96, v103, s92, v14
	v_add_u32_e32 v98, v14, v34
	v_mad_u32_u24 v100, v102, s92, v14
	v_mad_u32_u24 v109, v106, s92, v14
	v_mov_b32_e32 v15, s21
	v_or_b32_e32 v14, s20, v108
	v_mov_b32_e32 v70, s67
	v_mov_b32_e32 v71, s65
	v_mov_b32_e32 v72, s66
	v_mov_b32_e32 v73, s64
	v_cndmask_b32_e32 v35, v70, v71, vcc
	v_cndmask_b32_e32 v34, v72, v73, vcc
	v_lshlrev_b64 v[14:15], 12, v[14:15]
	v_lshl_add_u64 v[34:35], v[34:35], 0, v[14:15]
	s_lshl_b32 s4, s97, 8
	s_mov_b32 s5, s40
	v_lshl_add_u64 v[34:35], v[34:35], 0, s[4:5]
	v_lshlrev_b32_e32 v56, 1, v58
	v_mov_b32_e32 v57, v115
	v_lshl_add_u64 v[58:59], v[34:35], 0, v[56:57]
	v_mov_b32_e32 v35, s21
	v_or_b32_e32 v34, s20, v107
	v_cndmask_b32_e64 v61, v70, v71, s[8:9]
	v_cndmask_b32_e64 v60, v72, v73, s[8:9]
	v_lshlrev_b64 v[34:35], 12, v[34:35]
	v_lshl_add_u64 v[34:35], v[60:61], 0, v[34:35]
	v_lshl_add_u64 v[34:35], v[34:35], 0, s[4:5]
	v_lshl_add_u64 v[60:61], v[34:35], 0, v[56:57]
	v_mov_b32_e32 v35, s21
	v_or_b32_e32 v34, s20, v104
	v_cndmask_b32_e64 v63, v70, v71, s[10:11]
	v_cndmask_b32_e64 v62, v72, v73, s[10:11]
	v_lshlrev_b64 v[34:35], 12, v[34:35]
	v_lshl_add_u64 v[34:35], v[62:63], 0, v[34:35]
	v_lshl_add_u64 v[34:35], v[34:35], 0, s[4:5]
	v_lshl_add_u64 v[62:63], v[34:35], 0, v[56:57]
	v_mov_b32_e32 v35, s21
	v_or_b32_e32 v34, s20, v103
	v_cndmask_b32_e64 v65, v70, v71, s[16:17]
	v_cndmask_b32_e64 v64, v72, v73, s[16:17]
	v_lshlrev_b64 v[34:35], 12, v[34:35]
	v_lshl_add_u64 v[34:35], v[64:65], 0, v[34:35]
	v_lshl_add_u64 v[34:35], v[34:35], 0, s[4:5]
	v_lshl_add_u64 v[64:65], v[34:35], 0, v[56:57]
	v_cndmask_b32_e64 v35, v70, v71, s[12:13]
	v_cndmask_b32_e64 v34, v72, v73, s[12:13]
	v_lshl_add_u64 v[14:15], v[34:35], 0, v[14:15]
	v_lshl_add_u64 v[14:15], v[14:15], 0, s[4:5]
	v_lshl_add_u64 v[66:67], v[14:15], 0, v[56:57]
	v_mov_b32_e32 v15, s21
	v_or_b32_e32 v14, s20, v102
	v_cndmask_b32_e64 v35, v70, v71, s[14:15]
	v_cndmask_b32_e64 v34, v72, v73, s[14:15]
	v_lshlrev_b64 v[14:15], 12, v[14:15]
	v_lshl_add_u64 v[14:15], v[34:35], 0, v[14:15]
	s_waitcnt vmcnt(22)
	v_cvt_pk_bf16_f32 v6, v6, v7
	v_cvt_pk_bf16_f32 v7, v8, v9
	v_cvt_pk_bf16_f32 v8, v2, v3
	v_cndmask_b32_e32 v2, v94, v90, vcc
	v_add_u32_e32 v92, 0x1100, v90
	v_add_u32_e32 v95, 0x2200, v90
	v_add_u32_e32 v97, 0x3300, v90
	v_add_u32_e32 v101, 0x5500, v90
	v_add_u32_e32 v121, 0x6600, v90
	v_lshl_add_u64 v[14:15], v[14:15], 0, s[4:5]
	v_cvt_pk_bf16_f32 v9, v4, v5
	v_add_u32_e32 v90, 0, v2
	v_lshl_add_u64 v[68:69], v[14:15], 0, v[56:57]
	v_mov_b32_e32 v15, s21
	v_or_b32_e32 v14, s20, v106
	ds_write_b128 v90, v[6:9] offset:35840
	v_cndmask_b32_e64 v6, v91, v92, s[8:9]
	v_cndmask_b32_e64 v35, v70, v71, s[18:19]
	v_cndmask_b32_e64 v34, v72, v73, s[18:19]
	v_lshlrev_b64 v[14:15], 12, v[14:15]
	s_waitcnt vmcnt(20)
	v_cvt_pk_bf16_f32 v2, v16, v17
	v_cvt_pk_bf16_f32 v3, v18, v19
	v_cvt_pk_bf16_f32 v4, v10, v11
	v_cvt_pk_bf16_f32 v5, v12, v13
	v_add_u32_e32 v91, 0, v6
	v_cndmask_b32_e64 v6, v93, v95, s[10:11]
	v_lshl_add_u64 v[14:15], v[34:35], 0, v[14:15]
	ds_write_b128 v91, v[2:5] offset:35840
	s_waitcnt vmcnt(18)
	v_cvt_pk_bf16_f32 v2, v24, v25
	v_cvt_pk_bf16_f32 v3, v26, v27
	v_cvt_pk_bf16_f32 v4, v20, v21
	v_cvt_pk_bf16_f32 v5, v22, v23
	v_add_u32_e32 v92, 0, v6
	v_cndmask_b32_e64 v6, v96, v97, s[16:17]
	v_lshl_add_u64 v[14:15], v[14:15], 0, s[4:5]
	ds_write_b128 v92, v[2:5] offset:35840
	s_waitcnt vmcnt(16)
	v_cvt_pk_bf16_f32 v2, v36, v37
	v_cvt_pk_bf16_f32 v3, v38, v39
	v_cvt_pk_bf16_f32 v4, v28, v29
	v_cvt_pk_bf16_f32 v5, v30, v31
	v_add_u32_e32 v93, 0, v6
	v_cndmask_b32_e64 v6, v94, v98, s[12:13]
	v_lshl_add_u64 v[70:71], v[14:15], 0, v[56:57]
	v_mov_b32_e32 v15, s21
	v_or_b32_e32 v14, s20, v105
	ds_write_b128 v93, v[2:5] offset:35840
	s_waitcnt vmcnt(14)
	v_cvt_pk_bf16_f32 v2, v44, v45
	v_cvt_pk_bf16_f32 v3, v46, v47
	v_cvt_pk_bf16_f32 v4, v40, v41
	v_cvt_pk_bf16_f32 v5, v42, v43
	v_add_u32_e32 v94, 0, v6
	v_cndmask_b32_e64 v6, v100, v101, s[14:15]
	v_lshlrev_b64 v[14:15], 12, v[14:15]
	ds_write_b128 v94, v[2:5] offset:35840
	s_waitcnt vmcnt(12)
	v_cvt_pk_bf16_f32 v2, v52, v53
	v_cvt_pk_bf16_f32 v3, v54, v55
	v_cvt_pk_bf16_f32 v4, v48, v49
	v_cvt_pk_bf16_f32 v5, v50, v51
	v_add_u32_e32 v95, 0, v6
	v_cndmask_b32_e64 v6, v109, v121, s[18:19]
	v_lshl_add_u64 v[14:15], v[32:33], 0, v[14:15]
	ds_write_b128 v95, v[2:5] offset:35840
	s_waitcnt vmcnt(10)
	v_cvt_pk_bf16_f32 v2, v116, v117
	v_cvt_pk_bf16_f32 v3, v118, v119
	v_cvt_pk_bf16_f32 v4, v110, v111
	v_cvt_pk_bf16_f32 v5, v112, v113
	v_add_u32_e32 v96, 0, v6
	v_lshl_add_u64 v[14:15], v[14:15], 0, s[4:5]
	ds_write_b128 v96, v[2:5] offset:35840
	s_waitcnt vmcnt(8)
	v_cvt_pk_bf16_f32 v2, v126, v127
	v_cvt_pk_bf16_f32 v3, v128, v129
	v_cvt_pk_bf16_f32 v4, v122, v123
	v_cvt_pk_bf16_f32 v5, v124, v125
	s_or_b32 s4, s42, 0x80
	ds_write_b128 v99, v[2:5] offset:35840
	v_mov_b32_e32 v3, s43
	v_or_b32_e32 v2, s4, v108
	v_lshlrev_b64 v[34:35], 13, v[2:3]
	s_waitcnt vmcnt(0)
; #define LAS __attribute__((address_space(3)))
; __device__ __forceinline__ unsigned pk2(float lo, float hi) { const f32x2 v = {lo, hi}; return __builtin_bit_cast(unsigned, __builtin_convertvector(v, bf16x2_t)); }
; template <bool SAMP>
; __device__ __forceinline__ void attn_unit2(const Args& a, LAS unsigned char* lds, int n, int cch, int h) {
;     ...
;         auto tile_load = [&](int kc) {
;             if (SAMP && kc < 8) {
; #pragma unroll
;                 for (int p = 0; p < 8; ++p) { const int r = prow + 16 * p, kv = r >> 6, key = r & 63;
;                     const float* src = a.in[kv ? 5 : 4] + (((size_t)n * 512 + (size_t)kc * 64 + key) * NH + h) * HD + 8 * scc; R[2 * p] = *(const f32x4*)src; R[2 * p + 1] = *(const f32x4*)(src + 4); }
;             } else {
; #pragma unroll
;                 for (int p = 0; p < 8; ++p) { const int r = prow + 16 * p, kv = r >> 6, key = r & 63;
;                     const size_t krow = SAMP ? (size_t)MP + (size_t)n * 64 + key : (size_t)n * SEQ + (size_t)kc * 64 + key;
;                     R[p] = __builtin_bit_cast(f32x4, *(const u32x4*)((kv ? Vb : Kb) + krow * D + h * HD + 8 * scc)); } }
;         };
;         auto tile_store = [&](int kc, int buf) {
;             LAS unsigned char* bb = lds + buf * AT2_BUF;
; #pragma unroll
;             for (int p = 0; p < 8; ++p) { const int r = prow + 16 * p, kv = r >> 6, key = r & 63; u32x4 w;
;                 if (SAMP && kc < 8) { const f32x4 x0 = R[2 * p], x1 = R[2 * p + 1]; w.x = pk2(x0[0], x0[1]); w.y = pk2(x0[2], x0[3]); w.z = pk2(x1[0], x1[1]); w.w = pk2(x1[2], x1[3]); }
;                 else w = __builtin_bit_cast(u32x4, R[p]);
;                 *(LAS u32x4*)(bb + (kv ? AT_TILE + (key * AT_VS + 8 * scc) * 2 : (key * AT_KS + 8 * scc) * 2)) = w; }
;     ...
;         for (int kc = k0; kc <= k1; ++kc) {
;             if (kc < k1) { tile_store(kc + 1, (kc - k0 + 1) & 1); if (kc + 1 < k1) tile_load(kc + 2); }
;             __syncthreads(); }
	v_lshl_add_u64 v[2:3], v[74:75], 0, v[34:35]
	v_lshl_add_u64 v[2:3], v[2:3], 0, s[2:3]
	v_lshl_add_u64 v[6:7], v[2:3], 0, v[114:115]
	global_load_dwordx4 v[2:5], v[6:7], off offset:16
	s_nop 0
	global_load_dwordx4 v[6:9], v[6:7], off
	v_mov_b32_e32 v11, s43
	v_or_b32_e32 v10, s4, v107
	v_lshlrev_b64 v[10:11], 13, v[10:11]
	v_lshl_add_u64 v[72:73], v[14:15], 0, v[56:57]
	v_mov_b32_e32 v19, s43
	v_or_b32_e32 v18, s4, v104
	v_lshlrev_b64 v[18:19], 13, v[18:19]
	v_mov_b32_e32 v27, s43
	v_or_b32_e32 v26, s4, v103
	v_lshlrev_b64 v[26:27], 13, v[26:27]
	v_mov_b32_e32 v43, s43
	v_or_b32_e32 v42, s4, v102
	v_lshlrev_b64 v[42:43], 13, v[42:43]
	v_mov_b32_e32 v51, s43
	v_or_b32_e32 v50, s4, v106
	v_lshlrev_b64 v[50:51], 13, v[50:51]
	v_mov_b32_e32 v101, s43
	v_or_b32_e32 v100, s4, v105
	v_lshlrev_b64 v[100:101], 13, v[100:101]
	s_or_b32 s4, s42, 0xc0
	v_lshl_add_u64 v[10:11], v[76:77], 0, v[10:11]
	v_lshl_add_u64 v[10:11], v[10:11], 0, s[2:3]
	v_lshl_add_u64 v[14:15], v[10:11], 0, v[114:115]
	global_load_dwordx4 v[10:13], v[14:15], off offset:16
	s_nop 0
	global_load_dwordx4 v[14:17], v[14:15], off
	v_lshl_add_u64 v[18:19], v[78:79], 0, v[18:19]
	v_lshl_add_u64 v[18:19], v[18:19], 0, s[2:3]
	v_lshl_add_u64 v[22:23], v[18:19], 0, v[114:115]
	global_load_dwordx4 v[18:21], v[22:23], off offset:16
	s_nop 0
	global_load_dwordx4 v[22:25], v[22:23], off
	v_lshl_add_u64 v[26:27], v[80:81], 0, v[26:27]
	v_lshl_add_u64 v[26:27], v[26:27], 0, s[2:3]
	v_lshl_add_u64 v[30:31], v[26:27], 0, v[114:115]
	global_load_dwordx4 v[26:29], v[30:31], off offset:16
	s_nop 0
	global_load_dwordx4 v[30:33], v[30:31], off
	v_lshl_add_u64 v[34:35], v[82:83], 0, v[34:35]
	v_lshl_add_u64 v[34:35], v[34:35], 0, s[2:3]
	v_lshl_add_u64 v[38:39], v[34:35], 0, v[114:115]
	global_load_dwordx4 v[34:37], v[38:39], off offset:16
	s_nop 0
	global_load_dwordx4 v[38:41], v[38:39], off
	v_lshl_add_u64 v[42:43], v[84:85], 0, v[42:43]
	v_lshl_add_u64 v[42:43], v[42:43], 0, s[2:3]
	v_lshl_add_u64 v[46:47], v[42:43], 0, v[114:115]
	global_load_dwordx4 v[42:45], v[46:47], off offset:16
	s_nop 0
	global_load_dwordx4 v[46:49], v[46:47], off
	v_lshl_add_u64 v[50:51], v[86:87], 0, v[50:51]
	v_lshl_add_u64 v[50:51], v[50:51], 0, s[2:3]
	v_lshl_add_u64 v[54:55], v[50:51], 0, v[114:115]
	global_load_dwordx4 v[50:53], v[54:55], off offset:16
	s_nop 0
	global_load_dwordx4 v[54:57], v[54:55], off
	s_nop 0
	v_lshl_add_u64 v[100:101], v[88:89], 0, v[100:101]
	v_lshl_add_u64 v[100:101], v[100:101], 0, s[2:3]
	v_lshl_add_u64 v[100:101], v[100:101], 0, v[114:115]
	global_load_dwordx4 v[110:113], v[100:101], off offset:16
	global_load_dwordx4 v[116:119], v[100:101], off
	s_waitcnt lgkmcnt(0)
	s_barrier
	s_waitcnt vmcnt(14)
	v_cvt_pk_bf16_f32 v6, v6, v7
	v_cvt_pk_bf16_f32 v7, v8, v9
	v_cvt_pk_bf16_f32 v8, v2, v3
	v_cvt_pk_bf16_f32 v9, v4, v5
	s_waitcnt vmcnt(12)
	v_cvt_pk_bf16_f32 v4, v10, v11
	v_cvt_pk_bf16_f32 v2, v14, v15
	v_cvt_pk_bf16_f32 v3, v16, v17
	v_cvt_pk_bf16_f32 v5, v12, v13
	v_mov_b32_e32 v11, s43
	v_or_b32_e32 v10, s4, v107
	v_lshlrev_b64 v[10:11], 13, v[10:11]
	v_lshl_add_u64 v[10:11], v[76:77], 0, v[10:11]
	v_lshl_add_u64 v[10:11], v[10:11], 0, s[2:3]
	v_lshl_add_u64 v[14:15], v[10:11], 0, v[114:115]
	ds_write_b128 v90, v[6:9]
	ds_write_b128 v91, v[2:5]
	s_waitcnt vmcnt(10)
	v_cvt_pk_bf16_f32 v2, v22, v23
	v_cvt_pk_bf16_f32 v3, v24, v25
	v_cvt_pk_bf16_f32 v4, v18, v19
	v_cvt_pk_bf16_f32 v5, v20, v21
	ds_write_b128 v92, v[2:5]
	s_waitcnt vmcnt(8)
	v_cvt_pk_bf16_f32 v2, v30, v31
	v_cvt_pk_bf16_f32 v3, v32, v33
	v_cvt_pk_bf16_f32 v4, v26, v27
	v_cvt_pk_bf16_f32 v5, v28, v29
	ds_write_b128 v93, v[2:5]
	s_waitcnt vmcnt(6)
	v_cvt_pk_bf16_f32 v2, v38, v39
	v_cvt_pk_bf16_f32 v3, v40, v41
	v_cvt_pk_bf16_f32 v4, v34, v35
	v_cvt_pk_bf16_f32 v5, v36, v37
	ds_write_b128 v94, v[2:5]
	s_waitcnt vmcnt(4)
	v_cvt_pk_bf16_f32 v2, v46, v47
	v_cvt_pk_bf16_f32 v3, v48, v49
	v_cvt_pk_bf16_f32 v4, v42, v43
	v_cvt_pk_bf16_f32 v5, v44, v45
	ds_write_b128 v95, v[2:5]
	s_waitcnt vmcnt(2)
	v_cvt_pk_bf16_f32 v2, v54, v55
	v_cvt_pk_bf16_f32 v3, v56, v57
	v_cvt_pk_bf16_f32 v4, v50, v51
	v_cvt_pk_bf16_f32 v5, v52, v53
	ds_write_b128 v96, v[2:5]
	v_mov_b32_e32 v19, s43
	v_or_b32_e32 v18, s4, v104
	v_lshlrev_b64 v[18:19], 13, v[18:19]
	v_mov_b32_e32 v27, s43
	v_or_b32_e32 v26, s4, v103
	v_lshl_add_u64 v[18:19], v[78:79], 0, v[18:19]
	v_lshlrev_b64 v[26:27], 13, v[26:27]
	v_lshl_add_u64 v[18:19], v[18:19], 0, s[2:3]
	v_lshl_add_u64 v[26:27], v[80:81], 0, v[26:27]
	v_mov_b32_e32 v43, s43
	v_or_b32_e32 v42, s4, v102
	v_lshl_add_u64 v[22:23], v[18:19], 0, v[114:115]
	v_lshl_add_u64 v[26:27], v[26:27], 0, s[2:3]
	v_lshlrev_b64 v[42:43], 13, v[42:43]
	v_mov_b32_e32 v51, s43
	v_or_b32_e32 v50, s4, v106
	v_lshl_add_u64 v[30:31], v[26:27], 0, v[114:115]
	v_lshl_add_u64 v[42:43], v[84:85], 0, v[42:43]
	v_lshlrev_b64 v[50:51], 13, v[50:51]
	v_mov_b32_e32 v101, s43
	v_or_b32_e32 v100, s4, v105
	v_lshl_add_u64 v[42:43], v[42:43], 0, s[2:3]
	v_lshl_add_u64 v[50:51], v[86:87], 0, v[50:51]
	v_lshlrev_b64 v[100:101], 13, v[100:101]
	v_lshl_add_u64 v[46:47], v[42:43], 0, v[114:115]
	v_lshl_add_u64 v[50:51], v[50:51], 0, s[2:3]
	v_lshl_add_u64 v[100:101], v[88:89], 0, v[100:101]
	v_lshl_add_u64 v[54:55], v[50:51], 0, v[114:115]
	v_lshl_add_u64 v[100:101], v[100:101], 0, s[2:3]
	v_lshl_add_u64 v[100:101], v[100:101], 0, v[114:115]
	s_waitcnt vmcnt(1)
	v_cvt_pk_bf16_f32 v4, v110, v111
	s_waitcnt vmcnt(0)
	v_cvt_pk_bf16_f32 v2, v116, v117
	v_cvt_pk_bf16_f32 v3, v118, v119
	v_cvt_pk_bf16_f32 v5, v112, v113
	ds_write_b128 v99, v[2:5]
	v_mov_b32_e32 v3, s43
	v_or_b32_e32 v2, s4, v108
	v_lshlrev_b64 v[34:35], 13, v[2:3]
	v_lshl_add_u64 v[2:3], v[74:75], 0, v[34:35]
	v_lshl_add_u64 v[2:3], v[2:3], 0, s[2:3]
	v_lshl_add_u64 v[6:7], v[2:3], 0, v[114:115]
	global_load_dwordx4 v[2:5], v[6:7], off offset:16
	s_nop 0
	global_load_dwordx4 v[6:9], v[6:7], off
	s_nop 0
	global_load_dwordx4 v[10:13], v[14:15], off offset:16
	s_nop 0
	global_load_dwordx4 v[14:17], v[14:15], off
	v_lshl_add_u64 v[34:35], v[82:83], 0, v[34:35]
	global_load_dwordx4 v[18:21], v[22:23], off offset:16
	s_nop 0
	global_load_dwordx4 v[22:25], v[22:23], off
	v_lshl_add_u64 v[34:35], v[34:35], 0, s[2:3]
	global_load_dwordx4 v[26:29], v[30:31], off offset:16
	s_nop 0
	global_load_dwordx4 v[30:33], v[30:31], off
	v_lshl_add_u64 v[38:39], v[34:35], 0, v[114:115]
	global_load_dwordx4 v[34:37], v[38:39], off offset:16
	s_nop 0
	global_load_dwordx4 v[38:41], v[38:39], off
	s_nop 0
	global_load_dwordx4 v[42:45], v[46:47], off offset:16
	s_nop 0
	global_load_dwordx4 v[46:49], v[46:47], off
	s_nop 0
	global_load_dwordx4 v[50:53], v[54:55], off offset:16
	s_nop 0
	global_load_dwordx4 v[54:57], v[54:55], off
	s_nop 0
	global_load_dwordx4 v[110:113], v[100:101], off offset:16
	global_load_dwordx4 v[116:119], v[100:101], off
	s_waitcnt lgkmcnt(0)
	s_barrier
; #define LAS __attribute__((address_space(3)))
; __device__ __forceinline__ unsigned pk2(float lo, float hi) { const f32x2 v = {lo, hi}; return __builtin_bit_cast(unsigned, __builtin_convertvector(v, bf16x2_t)); }
; template <bool SAMP>
; __device__ __forceinline__ void attn_unit2(const Args& a, LAS unsigned char* lds, int n, int cch, int h) {
;     ...
;         auto tile_load = [&](int kc) {
;             if (SAMP && kc < 8) {
; #pragma unroll
;                 for (int p = 0; p < 8; ++p) { const int r = prow + 16 * p, kv = r >> 6, key = r & 63;
;                     const float* src = a.in[kv ? 5 : 4] + (((size_t)n * 512 + (size_t)kc * 64 + key) * NH + h) * HD + 8 * scc; R[2 * p] = *(const f32x4*)src; R[2 * p + 1] = *(const f32x4*)(src + 4); }
;             } else {
; #pragma unroll
;                 for (int p = 0; p < 8; ++p) { const int r = prow + 16 * p, kv = r >> 6, key = r & 63;
;                     const size_t krow = SAMP ? (size_t)MP + (size_t)n * 64 + key : (size_t)n * SEQ + (size_t)kc * 64 + key;
;                     R[p] = __builtin_bit_cast(f32x4, *(const u32x4*)((kv ? Vb : Kb) + krow * D + h * HD + 8 * scc)); } }
;     ...
;         auto tile_store = [&](int kc, int buf) {
;             LAS unsigned char* bb = lds + buf * AT2_BUF;
; #pragma unroll
;             for (int p = 0; p < 8; ++p) { const int r = prow + 16 * p, kv = r >> 6, key = r & 63; u32x4 w;
;                 if (SAMP && kc < 8) { const f32x4 x0 = R[2 * p], x1 = R[2 * p + 1]; w.x = pk2(x0[0], x0[1]); w.y = pk2(x0[2], x0[3]); w.z = pk2(x1[0], x1[1]); w.w = pk2(x1[2], x1[3]); }
;                 else w = __builtin_bit_cast(u32x4, R[p]);
;                 *(LAS u32x4*)(bb + (kv ? AT_TILE + (key * AT_VS + 8 * scc) * 2 : (key * AT_KS + 8 * scc) * 2)) = w; }
;     ...
;         for (int kc = k0; kc <= k1; ++kc) {
;             if (kc < k1) { tile_store(kc + 1, (kc - k0 + 1) & 1); if (kc + 1 < k1) tile_load(kc + 2); }
;             __syncthreads(); }
	s_or_b32 s4, s42, 0x100
	v_mov_b32_e32 v101, s43
	v_or_b32_e32 v100, s4, v105
	v_lshlrev_b64 v[100:101], 13, v[100:101]
	v_lshl_add_u64 v[100:101], v[88:89], 0, v[100:101]
	v_lshl_add_u64 v[100:101], v[100:101], 0, s[2:3]
	v_lshl_add_u64 v[100:101], v[100:101], 0, v[114:115]
	s_waitcnt vmcnt(14)
	v_cvt_pk_bf16_f32 v6, v6, v7
	v_cvt_pk_bf16_f32 v7, v8, v9
	v_cvt_pk_bf16_f32 v8, v2, v3
	v_cvt_pk_bf16_f32 v9, v4, v5
	s_waitcnt vmcnt(12)
	v_cvt_pk_bf16_f32 v2, v14, v15
	v_cvt_pk_bf16_f32 v3, v16, v17
	v_cvt_pk_bf16_f32 v4, v10, v11
	v_cvt_pk_bf16_f32 v5, v12, v13
	ds_write_b128 v90, v[6:9] offset:35840
	ds_write_b128 v91, v[2:5] offset:35840
	s_waitcnt vmcnt(10)
	v_cvt_pk_bf16_f32 v2, v22, v23
	v_cvt_pk_bf16_f32 v3, v24, v25
	v_cvt_pk_bf16_f32 v4, v18, v19
	v_cvt_pk_bf16_f32 v5, v20, v21
	ds_write_b128 v92, v[2:5] offset:35840
	s_waitcnt vmcnt(8)
	v_cvt_pk_bf16_f32 v2, v30, v31
	v_cvt_pk_bf16_f32 v3, v32, v33
	v_cvt_pk_bf16_f32 v4, v26, v27
	v_cvt_pk_bf16_f32 v5, v28, v29
	ds_write_b128 v93, v[2:5] offset:35840
	s_waitcnt vmcnt(6)
	v_cvt_pk_bf16_f32 v2, v38, v39
	v_cvt_pk_bf16_f32 v3, v40, v41
	v_cvt_pk_bf16_f32 v4, v34, v35
	v_cvt_pk_bf16_f32 v5, v36, v37
	ds_write_b128 v94, v[2:5] offset:35840
	s_waitcnt vmcnt(4)
	v_cvt_pk_bf16_f32 v2, v46, v47
	v_cvt_pk_bf16_f32 v3, v48, v49
	v_cvt_pk_bf16_f32 v4, v42, v43
	v_cvt_pk_bf16_f32 v5, v44, v45
	ds_write_b128 v95, v[2:5] offset:35840
	s_waitcnt vmcnt(2)
	v_cvt_pk_bf16_f32 v2, v54, v55
	v_cvt_pk_bf16_f32 v3, v56, v57
	v_cvt_pk_bf16_f32 v4, v50, v51
	v_cvt_pk_bf16_f32 v5, v52, v53
	ds_write_b128 v96, v[2:5] offset:35840
	s_waitcnt vmcnt(0)
	v_cvt_pk_bf16_f32 v2, v116, v117
	v_cvt_pk_bf16_f32 v3, v118, v119
	v_cvt_pk_bf16_f32 v4, v110, v111
	v_cvt_pk_bf16_f32 v5, v112, v113
	ds_write_b128 v99, v[2:5] offset:35840
	v_mov_b32_e32 v3, s43
	v_or_b32_e32 v2, s4, v108
	v_mov_b32_e32 v11, s43
	v_or_b32_e32 v10, s4, v107
	v_lshlrev_b64 v[34:35], 13, v[2:3]
	v_lshlrev_b64 v[10:11], 13, v[10:11]
	v_mov_b32_e32 v19, s43
	v_or_b32_e32 v18, s4, v104
	v_lshl_add_u64 v[2:3], v[74:75], 0, v[34:35]
	v_lshl_add_u64 v[10:11], v[76:77], 0, v[10:11]
	v_lshlrev_b64 v[18:19], 13, v[18:19]
	v_mov_b32_e32 v27, s43
	v_or_b32_e32 v26, s4, v103
	v_lshl_add_u64 v[2:3], v[2:3], 0, s[2:3]
	v_lshl_add_u64 v[10:11], v[10:11], 0, s[2:3]
	v_lshl_add_u64 v[18:19], v[78:79], 0, v[18:19]
	v_lshlrev_b64 v[26:27], 13, v[26:27]
	v_lshl_add_u64 v[6:7], v[2:3], 0, v[114:115]
	v_lshl_add_u64 v[14:15], v[10:11], 0, v[114:115]
	v_lshl_add_u64 v[18:19], v[18:19], 0, s[2:3]
	v_lshl_add_u64 v[26:27], v[80:81], 0, v[26:27]
	v_mov_b32_e32 v43, s43
	v_or_b32_e32 v42, s4, v102
	global_load_dwordx4 v[2:5], v[6:7], off offset:16
	s_nop 0
	global_load_dwordx4 v[6:9], v[6:7], off
	s_nop 0
	global_load_dwordx4 v[10:13], v[14:15], off offset:16
	s_nop 0
	global_load_dwordx4 v[14:17], v[14:15], off
	v_lshl_add_u64 v[22:23], v[18:19], 0, v[114:115]
	v_lshl_add_u64 v[26:27], v[26:27], 0, s[2:3]
	v_lshl_add_u64 v[34:35], v[82:83], 0, v[34:35]
	v_lshlrev_b64 v[42:43], 13, v[42:43]
	v_mov_b32_e32 v51, s43
	v_or_b32_e32 v50, s4, v106
	global_load_dwordx4 v[18:21], v[22:23], off offset:16
	s_nop 0
	global_load_dwordx4 v[22:25], v[22:23], off
	v_lshl_add_u64 v[30:31], v[26:27], 0, v[114:115]
	v_lshl_add_u64 v[34:35], v[34:35], 0, s[2:3]
	v_lshl_add_u64 v[42:43], v[84:85], 0, v[42:43]
	v_lshlrev_b64 v[50:51], 13, v[50:51]
	global_load_dwordx4 v[26:29], v[30:31], off offset:16
	s_nop 0
	global_load_dwordx4 v[30:33], v[30:31], off
	v_lshl_add_u64 v[38:39], v[34:35], 0, v[114:115]
	v_lshl_add_u64 v[42:43], v[42:43], 0, s[2:3]
	v_lshl_add_u64 v[50:51], v[86:87], 0, v[50:51]
	global_load_dwordx4 v[34:37], v[38:39], off offset:16
	s_nop 0
	global_load_dwordx4 v[38:41], v[38:39], off
	v_lshl_add_u64 v[46:47], v[42:43], 0, v[114:115]
	v_lshl_add_u64 v[50:51], v[50:51], 0, s[2:3]
	global_load_dwordx4 v[42:45], v[46:47], off offset:16
	s_nop 0
	global_load_dwordx4 v[46:49], v[46:47], off
	v_lshl_add_u64 v[54:55], v[50:51], 0, v[114:115]
	global_load_dwordx4 v[50:53], v[54:55], off offset:16
	s_nop 0
	global_load_dwordx4 v[54:57], v[54:55], off
	s_nop 0
	global_load_dwordx4 v[110:113], v[100:101], off offset:16
	global_load_dwordx4 v[116:119], v[100:101], off
	s_waitcnt lgkmcnt(0)
	s_barrier
; #define LAS __attribute__((address_space(3)))
; __device__ __forceinline__ unsigned pk2(float lo, float hi) { const f32x2 v = {lo, hi}; return __builtin_bit_cast(unsigned, __builtin_convertvector(v, bf16x2_t)); }
; template <bool SAMP>
; __device__ __forceinline__ void attn_unit2(const Args& a, LAS unsigned char* lds, int n, int cch, int h) {
;     ...
;         auto tile_load = [&](int kc) {
;             if (SAMP && kc < 8) {
; #pragma unroll
;                 for (int p = 0; p < 8; ++p) { const int r = prow + 16 * p, kv = r >> 6, key = r & 63;
;                     const float* src = a.in[kv ? 5 : 4] + (((size_t)n * 512 + (size_t)kc * 64 + key) * NH + h) * HD + 8 * scc; R[2 * p] = *(const f32x4*)src; R[2 * p + 1] = *(const f32x4*)(src + 4); }
;             } else {
; #pragma unroll
;                 for (int p = 0; p < 8; ++p) { const int r = prow + 16 * p, kv = r >> 6, key = r & 63;
;                     const size_t krow = SAMP ? (size_t)MP + (size_t)n * 64 + key : (size_t)n * SEQ + (size_t)kc * 64 + key;
;                     R[p] = __builtin_bit_cast(f32x4, *(const u32x4*)((kv ? Vb : Kb) + krow * D + h * HD + 8 * scc)); } }
;     ...
;         auto tile_store = [&](int kc, int buf) {
;             LAS unsigned char* bb = lds + buf * AT2_BUF;
; #pragma unroll
;             for (int p = 0; p < 8; ++p) { const int r = prow + 16 * p, kv = r >> 6, key = r & 63; u32x4 w;
;                 if (SAMP && kc < 8) { const f32x4 x0 = R[2 * p], x1 = R[2 * p + 1]; w.x = pk2(x0[0], x0[1]); w.y = pk2(x0[2], x0[3]); w.z = pk2(x1[0], x1[1]); w.w = pk2(x1[2], x1[3]); }
;                 else w = __builtin_bit_cast(u32x4, R[p]);
;                 *(LAS u32x4*)(bb + (kv ? AT_TILE + (key * AT_VS + 8 * scc) * 2 : (key * AT_KS + 8 * scc) * 2)) = w; }
;     ...
;         for (int kc = k0; kc <= k1; ++kc) {
;             if (kc < k1) { tile_store(kc + 1, (kc - k0 + 1) & 1); if (kc + 1 < k1) tile_load(kc + 2); }
;             __syncthreads(); }
	s_or_b32 s4, s42, 0x140
	v_mov_b32_e32 v101, s43
	v_or_b32_e32 v100, s4, v105
	v_lshlrev_b64 v[100:101], 13, v[100:101]
	v_lshl_add_u64 v[100:101], v[88:89], 0, v[100:101]
	v_lshl_add_u64 v[100:101], v[100:101], 0, s[2:3]
	v_lshl_add_u64 v[100:101], v[100:101], 0, v[114:115]
	s_waitcnt vmcnt(14)
	v_cvt_pk_bf16_f32 v6, v6, v7
	v_cvt_pk_bf16_f32 v7, v8, v9
	v_cvt_pk_bf16_f32 v8, v2, v3
	v_cvt_pk_bf16_f32 v9, v4, v5
	s_waitcnt vmcnt(12)
	v_cvt_pk_bf16_f32 v2, v14, v15
	v_cvt_pk_bf16_f32 v3, v16, v17
	v_cvt_pk_bf16_f32 v4, v10, v11
	v_cvt_pk_bf16_f32 v5, v12, v13
	ds_write_b128 v90, v[6:9]
	ds_write_b128 v91, v[2:5]
	s_waitcnt vmcnt(10)
	v_cvt_pk_bf16_f32 v2, v22, v23
	v_cvt_pk_bf16_f32 v3, v24, v25
	v_cvt_pk_bf16_f32 v4, v18, v19
	v_cvt_pk_bf16_f32 v5, v20, v21
	ds_write_b128 v92, v[2:5]
	s_waitcnt vmcnt(8)
	v_cvt_pk_bf16_f32 v2, v30, v31
	v_cvt_pk_bf16_f32 v3, v32, v33
	v_cvt_pk_bf16_f32 v4, v26, v27
	v_cvt_pk_bf16_f32 v5, v28, v29
	ds_write_b128 v93, v[2:5]
	s_waitcnt vmcnt(6)
	v_cvt_pk_bf16_f32 v2, v38, v39
	v_cvt_pk_bf16_f32 v3, v40, v41
	v_cvt_pk_bf16_f32 v4, v34, v35
	v_cvt_pk_bf16_f32 v5, v36, v37
	ds_write_b128 v94, v[2:5]
	s_waitcnt vmcnt(4)
	v_cvt_pk_bf16_f32 v2, v46, v47
	v_cvt_pk_bf16_f32 v3, v48, v49
	v_cvt_pk_bf16_f32 v4, v42, v43
	v_cvt_pk_bf16_f32 v5, v44, v45
	ds_write_b128 v95, v[2:5]
	s_waitcnt vmcnt(2)
	v_cvt_pk_bf16_f32 v2, v54, v55
	v_cvt_pk_bf16_f32 v3, v56, v57
	v_cvt_pk_bf16_f32 v4, v50, v51
	v_cvt_pk_bf16_f32 v5, v52, v53
	ds_write_b128 v96, v[2:5]
	s_waitcnt vmcnt(0)
	v_cvt_pk_bf16_f32 v2, v116, v117
	v_cvt_pk_bf16_f32 v3, v118, v119
	v_cvt_pk_bf16_f32 v4, v110, v111
	v_cvt_pk_bf16_f32 v5, v112, v113
	ds_write_b128 v99, v[2:5]
	v_mov_b32_e32 v3, s43
	v_or_b32_e32 v2, s4, v108
	v_mov_b32_e32 v11, s43
	v_or_b32_e32 v10, s4, v107
	v_lshlrev_b64 v[34:35], 13, v[2:3]
	v_lshlrev_b64 v[10:11], 13, v[10:11]
	v_mov_b32_e32 v19, s43
	v_or_b32_e32 v18, s4, v104
	v_lshl_add_u64 v[2:3], v[74:75], 0, v[34:35]
	v_lshl_add_u64 v[10:11], v[76:77], 0, v[10:11]
	v_lshlrev_b64 v[18:19], 13, v[18:19]
	v_mov_b32_e32 v27, s43
	v_or_b32_e32 v26, s4, v103
	v_lshl_add_u64 v[2:3], v[2:3], 0, s[2:3]
	v_lshl_add_u64 v[10:11], v[10:11], 0, s[2:3]
	v_lshl_add_u64 v[18:19], v[78:79], 0, v[18:19]
	v_lshlrev_b64 v[26:27], 13, v[26:27]
	v_lshl_add_u64 v[6:7], v[2:3], 0, v[114:115]
	v_lshl_add_u64 v[14:15], v[10:11], 0, v[114:115]
	v_lshl_add_u64 v[18:19], v[18:19], 0, s[2:3]
	v_lshl_add_u64 v[26:27], v[80:81], 0, v[26:27]
	v_mov_b32_e32 v43, s43
	v_or_b32_e32 v42, s4, v102
	global_load_dwordx4 v[2:5], v[6:7], off offset:16
	s_nop 0
	global_load_dwordx4 v[6:9], v[6:7], off
	s_nop 0
	global_load_dwordx4 v[10:13], v[14:15], off offset:16
	s_nop 0
	global_load_dwordx4 v[14:17], v[14:15], off
	v_lshl_add_u64 v[22:23], v[18:19], 0, v[114:115]
	v_lshl_add_u64 v[26:27], v[26:27], 0, s[2:3]
	v_lshl_add_u64 v[34:35], v[82:83], 0, v[34:35]
	v_lshlrev_b64 v[42:43], 13, v[42:43]
	v_mov_b32_e32 v51, s43
	v_or_b32_e32 v50, s4, v106
	global_load_dwordx4 v[18:21], v[22:23], off offset:16
	s_nop 0
	global_load_dwordx4 v[22:25], v[22:23], off
	v_lshl_add_u64 v[30:31], v[26:27], 0, v[114:115]
	v_lshl_add_u64 v[34:35], v[34:35], 0, s[2:3]
	v_lshl_add_u64 v[42:43], v[84:85], 0, v[42:43]
	v_lshlrev_b64 v[50:51], 13, v[50:51]
	global_load_dwordx4 v[26:29], v[30:31], off offset:16
	s_nop 0
	global_load_dwordx4 v[30:33], v[30:31], off
	v_lshl_add_u64 v[38:39], v[34:35], 0, v[114:115]
	v_lshl_add_u64 v[42:43], v[42:43], 0, s[2:3]
	v_lshl_add_u64 v[50:51], v[86:87], 0, v[50:51]
	global_load_dwordx4 v[34:37], v[38:39], off offset:16
	s_nop 0
	global_load_dwordx4 v[38:41], v[38:39], off
	v_lshl_add_u64 v[46:47], v[42:43], 0, v[114:115]
	v_lshl_add_u64 v[50:51], v[50:51], 0, s[2:3]
	global_load_dwordx4 v[42:45], v[46:47], off offset:16
	s_nop 0
	global_load_dwordx4 v[46:49], v[46:47], off
	v_lshl_add_u64 v[54:55], v[50:51], 0, v[114:115]
	global_load_dwordx4 v[50:53], v[54:55], off offset:16
	s_nop 0
	global_load_dwordx4 v[54:57], v[54:55], off
	s_nop 0
	global_load_dwordx4 v[110:113], v[100:101], off offset:16
	global_load_dwordx4 v[116:119], v[100:101], off
	s_waitcnt lgkmcnt(0)
	s_barrier
	s_or_b32 s4, s42, 0x180
	v_mov_b32_e32 v101, s43
	v_or_b32_e32 v100, s4, v105
	v_lshlrev_b64 v[100:101], 13, v[100:101]
	v_lshl_add_u64 v[100:101], v[88:89], 0, v[100:101]
	v_lshl_add_u64 v[100:101], v[100:101], 0, s[2:3]
	v_lshl_add_u64 v[100:101], v[100:101], 0, v[114:115]
	s_waitcnt vmcnt(14)
	v_cvt_pk_bf16_f32 v6, v6, v7
	v_cvt_pk_bf16_f32 v7, v8, v9
	v_cvt_pk_bf16_f32 v8, v2, v3
	v_cvt_pk_bf16_f32 v9, v4, v5
	s_waitcnt vmcnt(12)
	v_cvt_pk_bf16_f32 v2, v14, v15
	v_cvt_pk_bf16_f32 v3, v16, v17
	v_cvt_pk_bf16_f32 v4, v10, v11
	v_cvt_pk_bf16_f32 v5, v12, v13
	ds_write_b128 v90, v[6:9] offset:35840
	ds_write_b128 v91, v[2:5] offset:35840
	s_waitcnt vmcnt(10)
	v_cvt_pk_bf16_f32 v2, v22, v23
	v_cvt_pk_bf16_f32 v3, v24, v25
	v_cvt_pk_bf16_f32 v4, v18, v19
	v_cvt_pk_bf16_f32 v5, v20, v21
	ds_write_b128 v92, v[2:5] offset:35840
	s_waitcnt vmcnt(8)
	v_cvt_pk_bf16_f32 v2, v30, v31
	v_cvt_pk_bf16_f32 v3, v32, v33
	v_cvt_pk_bf16_f32 v4, v26, v27
	v_cvt_pk_bf16_f32 v5, v28, v29
	ds_write_b128 v93, v[2:5] offset:35840
	s_waitcnt vmcnt(6)
	v_cvt_pk_bf16_f32 v2, v38, v39
	v_cvt_pk_bf16_f32 v3, v40, v41
	v_cvt_pk_bf16_f32 v4, v34, v35
	v_cvt_pk_bf16_f32 v5, v36, v37
	ds_write_b128 v94, v[2:5] offset:35840
	s_waitcnt vmcnt(4)
	v_cvt_pk_bf16_f32 v2, v46, v47
	v_cvt_pk_bf16_f32 v3, v48, v49
	v_cvt_pk_bf16_f32 v4, v42, v43
	v_cvt_pk_bf16_f32 v5, v44, v45
	ds_write_b128 v95, v[2:5] offset:35840
	s_waitcnt vmcnt(2)
; #define LAS __attribute__((address_space(3)))
; __device__ __forceinline__ unsigned pk2(float lo, float hi) { const f32x2 v = {lo, hi}; return __builtin_bit_cast(unsigned, __builtin_convertvector(v, bf16x2_t)); }
; template <bool SAMP>
; __device__ __forceinline__ void attn_unit2(const Args& a, LAS unsigned char* lds, int n, int cch, int h) {
;     ...
;         auto tile_load = [&](int kc) {
;             if (SAMP && kc < 8) {
; #pragma unroll
;                 for (int p = 0; p < 8; ++p) { const int r = prow + 16 * p, kv = r >> 6, key = r & 63;
;                     const float* src = a.in[kv ? 5 : 4] + (((size_t)n * 512 + (size_t)kc * 64 + key) * NH + h) * HD + 8 * scc; R[2 * p] = *(const f32x4*)src; R[2 * p + 1] = *(const f32x4*)(src + 4); }
;             } else {
; #pragma unroll
;                 for (int p = 0; p < 8; ++p) { const int r = prow + 16 * p, kv = r >> 6, key = r & 63;
;                     const size_t krow = SAMP ? (size_t)MP + (size_t)n * 64 + key : (size_t)n * SEQ + (size_t)kc * 64 + key;
;                     R[p] = __builtin_bit_cast(f32x4, *(const u32x4*)((kv ? Vb : Kb) + krow * D + h * HD + 8 * scc)); } }
;     ...
;         auto tile_store = [&](int kc, int buf) {
;             LAS unsigned char* bb = lds + buf * AT2_BUF;
; #pragma unroll
;             for (int p = 0; p < 8; ++p) { const int r = prow + 16 * p, kv = r >> 6, key = r & 63; u32x4 w;
;                 if (SAMP && kc < 8) { const f32x4 x0 = R[2 * p], x1 = R[2 * p + 1]; w.x = pk2(x0[0], x0[1]); w.y = pk2(x0[2], x0[3]); w.z = pk2(x1[0], x1[1]); w.w = pk2(x1[2], x1[3]); }
;                 else w = __builtin_bit_cast(u32x4, R[p]);
;                 *(LAS u32x4*)(bb + (kv ? AT_TILE + (key * AT_VS + 8 * scc) * 2 : (key * AT_KS + 8 * scc) * 2)) = w; }
;     ...
;             __syncthreads(); }
	v_cvt_pk_bf16_f32 v2, v54, v55
	v_cvt_pk_bf16_f32 v3, v56, v57
	v_cvt_pk_bf16_f32 v4, v50, v51
	v_cvt_pk_bf16_f32 v5, v52, v53
	ds_write_b128 v96, v[2:5] offset:35840
	s_waitcnt vmcnt(0)
	v_cvt_pk_bf16_f32 v2, v116, v117
	v_cvt_pk_bf16_f32 v3, v118, v119
	v_cvt_pk_bf16_f32 v4, v110, v111
	v_cvt_pk_bf16_f32 v5, v112, v113
	ds_write_b128 v99, v[2:5] offset:35840
	v_mov_b32_e32 v3, s43
	v_or_b32_e32 v2, s4, v108
	v_mov_b32_e32 v11, s43
	v_or_b32_e32 v10, s4, v107
	v_lshlrev_b64 v[34:35], 13, v[2:3]
	v_lshlrev_b64 v[10:11], 13, v[10:11]
	v_mov_b32_e32 v19, s43
	v_or_b32_e32 v18, s4, v104
	v_lshl_add_u64 v[2:3], v[74:75], 0, v[34:35]
	v_lshl_add_u64 v[10:11], v[76:77], 0, v[10:11]
	v_lshlrev_b64 v[18:19], 13, v[18:19]
	v_mov_b32_e32 v27, s43
	v_or_b32_e32 v26, s4, v103
	v_lshl_add_u64 v[2:3], v[2:3], 0, s[2:3]
	v_lshl_add_u64 v[10:11], v[10:11], 0, s[2:3]
	v_lshl_add_u64 v[18:19], v[78:79], 0, v[18:19]
	v_lshlrev_b64 v[26:27], 13, v[26:27]
	v_lshl_add_u64 v[6:7], v[2:3], 0, v[114:115]
	v_lshl_add_u64 v[14:15], v[10:11], 0, v[114:115]
	v_lshl_add_u64 v[18:19], v[18:19], 0, s[2:3]
	v_lshl_add_u64 v[26:27], v[80:81], 0, v[26:27]
	v_mov_b32_e32 v43, s43
	v_or_b32_e32 v42, s4, v102
	global_load_dwordx4 v[2:5], v[6:7], off offset:16
	s_nop 0
	global_load_dwordx4 v[6:9], v[6:7], off
	s_nop 0
	global_load_dwordx4 v[10:13], v[14:15], off offset:16
	s_nop 0
	global_load_dwordx4 v[14:17], v[14:15], off
	v_lshl_add_u64 v[22:23], v[18:19], 0, v[114:115]
	v_lshl_add_u64 v[26:27], v[26:27], 0, s[2:3]
	v_lshl_add_u64 v[34:35], v[82:83], 0, v[34:35]
	v_lshlrev_b64 v[42:43], 13, v[42:43]
	v_mov_b32_e32 v51, s43
	v_or_b32_e32 v50, s4, v106
	global_load_dwordx4 v[18:21], v[22:23], off offset:16
	s_nop 0
	global_load_dwordx4 v[22:25], v[22:23], off
	v_lshl_add_u64 v[30:31], v[26:27], 0, v[114:115]
	v_lshl_add_u64 v[34:35], v[34:35], 0, s[2:3]
	v_lshl_add_u64 v[42:43], v[84:85], 0, v[42:43]
	v_lshlrev_b64 v[50:51], 13, v[50:51]
	global_load_dwordx4 v[26:29], v[30:31], off offset:16
	s_nop 0
	global_load_dwordx4 v[30:33], v[30:31], off
	v_lshl_add_u64 v[38:39], v[34:35], 0, v[114:115]
	v_lshl_add_u64 v[42:43], v[42:43], 0, s[2:3]
	v_lshl_add_u64 v[50:51], v[86:87], 0, v[50:51]
	global_load_dwordx4 v[34:37], v[38:39], off offset:16
	s_nop 0
	global_load_dwordx4 v[38:41], v[38:39], off
	v_lshl_add_u64 v[46:47], v[42:43], 0, v[114:115]
	v_lshl_add_u64 v[50:51], v[50:51], 0, s[2:3]
	global_load_dwordx4 v[42:45], v[46:47], off offset:16
	s_nop 0
	global_load_dwordx4 v[46:49], v[46:47], off
	v_lshl_add_u64 v[54:55], v[50:51], 0, v[114:115]
	global_load_dwordx4 v[50:53], v[54:55], off offset:16
	s_nop 0
	global_load_dwordx4 v[54:57], v[54:55], off
	s_nop 0
	global_load_dwordx4 v[110:113], v[100:101], off offset:16
	global_load_dwordx4 v[116:119], v[100:101], off
	s_waitcnt lgkmcnt(0)
	s_barrier
; #define LAS __attribute__((address_space(3)))
; __device__ __forceinline__ unsigned pk2(float lo, float hi) { const f32x2 v = {lo, hi}; return __builtin_bit_cast(unsigned, __builtin_convertvector(v, bf16x2_t)); }
; template <bool SAMP>
; __device__ __forceinline__ void attn_unit2(const Args& a, LAS unsigned char* lds, int n, int cch, int h) {
;     ...
;         auto tile_load = [&](int kc) {
;             if (SAMP && kc < 8) {
; #pragma unroll
;                 for (int p = 0; p < 8; ++p) { const int r = prow + 16 * p, kv = r >> 6, key = r & 63;
;                     const float* src = a.in[kv ? 5 : 4] + (((size_t)n * 512 + (size_t)kc * 64 + key) * NH + h) * HD + 8 * scc; R[2 * p] = *(const f32x4*)src; R[2 * p + 1] = *(const f32x4*)(src + 4); }
;             } else {
; #pragma unroll
;                 for (int p = 0; p < 8; ++p) { const int r = prow + 16 * p, kv = r >> 6, key = r & 63;
;                     const size_t krow = SAMP ? (size_t)MP + (size_t)n * 64 + key : (size_t)n * SEQ + (size_t)kc * 64 + key;
;                     R[p] = __builtin_bit_cast(f32x4, *(const u32x4*)((kv ? Vb : Kb) + krow * D + h * HD + 8 * scc)); } }
;         };
;         auto tile_store = [&](int kc, int buf) {
;             LAS unsigned char* bb = lds + buf * AT2_BUF;
; #pragma unroll
;             for (int p = 0; p < 8; ++p) { const int r = prow + 16 * p, kv = r >> 6, key = r & 63; u32x4 w;
;                 if (SAMP && kc < 8) { const f32x4 x0 = R[2 * p], x1 = R[2 * p + 1]; w.x = pk2(x0[0], x0[1]); w.y = pk2(x0[2], x0[3]); w.z = pk2(x1[0], x1[1]); w.w = pk2(x1[2], x1[3]); }
;                 else w = __builtin_bit_cast(u32x4, R[p]);
;                 *(LAS u32x4*)(bb + (kv ? AT_TILE + (key * AT_VS + 8 * scc) * 2 : (key * AT_KS + 8 * scc) * 2)) = w; }
;         };
;         for (int i = tp; i < 257; i += 256) tabs[i] = a.in[18][(size_t)h * 257 + i] * 1.4426950408889634f;
;         tile_load(k0); tile_store(k0, 0);
;         if (k0 < k1) tile_load(k0 + 1);
;         __syncthreads();
;         for (int kc = k0; kc <= k1; ++kc) {
;             if (kc < k1) { tile_store(kc + 1, (kc - k0 + 1) & 1); if (kc + 1 < k1) tile_load(kc + 2); }
;             __syncthreads(); }
	s_or_b32 s4, s42, 0x1c0
	s_waitcnt vmcnt(14)
	v_cvt_pk_bf16_f32 v6, v6, v7
	v_cvt_pk_bf16_f32 v7, v8, v9
	v_cvt_pk_bf16_f32 v8, v2, v3
	v_cvt_pk_bf16_f32 v9, v4, v5
	s_waitcnt vmcnt(12)
	v_cvt_pk_bf16_f32 v2, v14, v15
	v_cvt_pk_bf16_f32 v3, v16, v17
	v_cvt_pk_bf16_f32 v4, v10, v11
	v_cvt_pk_bf16_f32 v5, v12, v13
	ds_write_b128 v90, v[6:9]
	ds_write_b128 v91, v[2:5]
	s_waitcnt vmcnt(10)
	v_cvt_pk_bf16_f32 v2, v22, v23
	v_cvt_pk_bf16_f32 v3, v24, v25
	v_cvt_pk_bf16_f32 v4, v18, v19
	v_cvt_pk_bf16_f32 v5, v20, v21
	ds_write_b128 v92, v[2:5]
	s_waitcnt vmcnt(8)
	v_cvt_pk_bf16_f32 v2, v30, v31
	v_cvt_pk_bf16_f32 v3, v32, v33
	v_cvt_pk_bf16_f32 v4, v26, v27
	v_cvt_pk_bf16_f32 v5, v28, v29
	ds_write_b128 v93, v[2:5]
	s_waitcnt vmcnt(6)
	v_cvt_pk_bf16_f32 v2, v38, v39
	v_cvt_pk_bf16_f32 v3, v40, v41
	v_cvt_pk_bf16_f32 v4, v34, v35
	v_cvt_pk_bf16_f32 v5, v36, v37
	ds_write_b128 v94, v[2:5]
	s_waitcnt vmcnt(4)
	v_cvt_pk_bf16_f32 v2, v46, v47
	v_cvt_pk_bf16_f32 v3, v48, v49
	v_cvt_pk_bf16_f32 v4, v42, v43
	v_cvt_pk_bf16_f32 v5, v44, v45
	ds_write_b128 v95, v[2:5]
	s_waitcnt vmcnt(2)
	v_cvt_pk_bf16_f32 v2, v54, v55
	v_cvt_pk_bf16_f32 v3, v56, v57
	v_cvt_pk_bf16_f32 v4, v50, v51
	v_cvt_pk_bf16_f32 v5, v52, v53
	ds_write_b128 v96, v[2:5]
	s_waitcnt vmcnt(0)
	v_cvt_pk_bf16_f32 v2, v116, v117
	v_cvt_pk_bf16_f32 v3, v118, v119
	v_cvt_pk_bf16_f32 v4, v110, v111
	v_cvt_pk_bf16_f32 v5, v112, v113
	ds_write_b128 v99, v[2:5]
	v_mov_b32_e32 v3, s43
	v_or_b32_e32 v2, s4, v108
	v_mov_b32_e32 v11, s43
	v_or_b32_e32 v10, s4, v107
	v_lshlrev_b64 v[34:35], 13, v[2:3]
	v_lshlrev_b64 v[10:11], 13, v[10:11]
	v_mov_b32_e32 v19, s43
	v_or_b32_e32 v18, s4, v104
	v_lshl_add_u64 v[2:3], v[74:75], 0, v[34:35]
	v_lshl_add_u64 v[10:11], v[76:77], 0, v[10:11]
	v_lshlrev_b64 v[18:19], 13, v[18:19]
	v_mov_b32_e32 v27, s43
	v_or_b32_e32 v26, s4, v103
	v_lshl_add_u64 v[2:3], v[2:3], 0, s[2:3]
	v_lshl_add_u64 v[10:11], v[10:11], 0, s[2:3]
	v_lshl_add_u64 v[18:19], v[78:79], 0, v[18:19]
	v_lshlrev_b64 v[26:27], 13, v[26:27]
	v_lshl_add_u64 v[6:7], v[2:3], 0, v[114:115]
	v_lshl_add_u64 v[14:15], v[10:11], 0, v[114:115]
	v_lshl_add_u64 v[18:19], v[18:19], 0, s[2:3]
	v_lshl_add_u64 v[26:27], v[80:81], 0, v[26:27]
	v_mov_b32_e32 v43, s43
	v_or_b32_e32 v42, s4, v102
	global_load_dwordx4 v[2:5], v[6:7], off offset:16
	s_nop 0
	global_load_dwordx4 v[6:9], v[6:7], off
	s_nop 0
	global_load_dwordx4 v[10:13], v[14:15], off offset:16
	s_nop 0
	global_load_dwordx4 v[14:17], v[14:15], off
	v_lshl_add_u64 v[22:23], v[18:19], 0, v[114:115]
	v_lshl_add_u64 v[26:27], v[26:27], 0, s[2:3]
	v_lshl_add_u64 v[34:35], v[82:83], 0, v[34:35]
	v_lshlrev_b64 v[42:43], 13, v[42:43]
	v_mov_b32_e32 v51, s43
	v_or_b32_e32 v50, s4, v106
	global_load_dwordx4 v[18:21], v[22:23], off offset:16
	s_nop 0
	global_load_dwordx4 v[22:25], v[22:23], off
	v_lshl_add_u64 v[30:31], v[26:27], 0, v[114:115]
	v_lshl_add_u64 v[34:35], v[34:35], 0, s[2:3]
	v_lshl_add_u64 v[42:43], v[84:85], 0, v[42:43]
	v_lshlrev_b64 v[50:51], 13, v[50:51]
	v_mov_b32_e32 v75, s43
	v_or_b32_e32 v74, s4, v105
	global_load_dwordx4 v[26:29], v[30:31], off offset:16
	s_nop 0
	global_load_dwordx4 v[30:33], v[30:31], off
	v_lshl_add_u64 v[38:39], v[34:35], 0, v[114:115]
	v_lshl_add_u64 v[42:43], v[42:43], 0, s[2:3]
	v_lshl_add_u64 v[50:51], v[86:87], 0, v[50:51]
	v_lshlrev_b64 v[74:75], 13, v[74:75]
	global_load_dwordx4 v[34:37], v[38:39], off offset:16
	s_nop 0
	global_load_dwordx4 v[38:41], v[38:39], off
	v_lshl_add_u64 v[46:47], v[42:43], 0, v[114:115]
	v_lshl_add_u64 v[50:51], v[50:51], 0, s[2:3]
	v_lshl_add_u64 v[74:75], v[88:89], 0, v[74:75]
	global_load_dwordx4 v[42:45], v[46:47], off offset:16
	s_nop 0
	global_load_dwordx4 v[46:49], v[46:47], off
	v_lshl_add_u64 v[54:55], v[50:51], 0, v[114:115]
	v_lshl_add_u64 v[74:75], v[74:75], 0, s[2:3]
	global_load_dwordx4 v[50:53], v[54:55], off offset:16
	s_nop 0
	global_load_dwordx4 v[54:57], v[54:55], off
	v_lshl_add_u64 v[78:79], v[74:75], 0, v[114:115]
	global_load_dwordx4 v[74:77], v[78:79], off offset:16
	s_nop 0
	global_load_dwordx4 v[78:81], v[78:79], off
	s_waitcnt lgkmcnt(0)
	s_barrier
	s_mov_b64 s[2:3], 0
	s_waitcnt vmcnt(14)
	v_cvt_pk_bf16_f32 v6, v6, v7
	v_cvt_pk_bf16_f32 v7, v8, v9
	v_cvt_pk_bf16_f32 v8, v2, v3
	v_cvt_pk_bf16_f32 v9, v4, v5
	s_waitcnt vmcnt(12)
	v_cvt_pk_bf16_f32 v2, v14, v15
	v_cvt_pk_bf16_f32 v3, v16, v17
	v_cvt_pk_bf16_f32 v4, v10, v11
	v_cvt_pk_bf16_f32 v5, v12, v13
	ds_write_b128 v90, v[6:9] offset:35840
	ds_write_b128 v91, v[2:5] offset:35840
	s_waitcnt vmcnt(10)
	v_cvt_pk_bf16_f32 v2, v22, v23
	v_cvt_pk_bf16_f32 v3, v24, v25
	v_cvt_pk_bf16_f32 v4, v18, v19
	v_cvt_pk_bf16_f32 v5, v20, v21
	ds_write_b128 v92, v[2:5] offset:35840
	s_waitcnt vmcnt(8)
	v_cvt_pk_bf16_f32 v2, v30, v31
	v_cvt_pk_bf16_f32 v3, v32, v33
	v_cvt_pk_bf16_f32 v4, v26, v27
	v_cvt_pk_bf16_f32 v5, v28, v29
	ds_write_b128 v93, v[2:5] offset:35840
	s_waitcnt vmcnt(6)
	v_cvt_pk_bf16_f32 v2, v38, v39
	v_cvt_pk_bf16_f32 v3, v40, v41
	v_cvt_pk_bf16_f32 v4, v34, v35
	v_cvt_pk_bf16_f32 v5, v36, v37
	ds_write_b128 v94, v[2:5] offset:35840
	s_waitcnt vmcnt(4)
	v_cvt_pk_bf16_f32 v2, v46, v47
	v_cvt_pk_bf16_f32 v3, v48, v49
	v_cvt_pk_bf16_f32 v4, v42, v43
	v_cvt_pk_bf16_f32 v5, v44, v45
	ds_write_b128 v95, v[2:5] offset:35840
	s_waitcnt vmcnt(2)
	v_cvt_pk_bf16_f32 v2, v54, v55
	v_cvt_pk_bf16_f32 v3, v56, v57
	v_cvt_pk_bf16_f32 v4, v50, v51
	v_cvt_pk_bf16_f32 v5, v52, v53
	ds_write_b128 v96, v[2:5] offset:35840
	s_waitcnt vmcnt(0)
	v_cvt_pk_bf16_f32 v2, v78, v79
	v_cvt_pk_bf16_f32 v3, v80, v81
	v_cvt_pk_bf16_f32 v4, v74, v75
	v_cvt_pk_bf16_f32 v5, v76, v77
	ds_write_b128 v99, v[2:5] offset:35840
	global_load_dwordx4 v[2:5], v[58:59], off
	global_load_dwordx4 v[6:9], v[60:61], off
	global_load_dwordx4 v[10:13], v[62:63], off
	global_load_dwordx4 v[14:17], v[64:65], off
	global_load_dwordx4 v[18:21], v[66:67], off
	global_load_dwordx4 v[22:25], v[68:69], off
	global_load_dwordx4 v[26:29], v[70:71], off
	global_load_dwordx4 v[30:33], v[72:73], off
	s_waitcnt lgkmcnt(0)
	s_barrier
	s_waitcnt vmcnt(7)
	ds_write_b128 v90, v[2:5]
	s_waitcnt vmcnt(6)
	ds_write_b128 v91, v[6:9]
	s_waitcnt vmcnt(5)
	ds_write_b128 v92, v[10:13]
	s_waitcnt vmcnt(4)
	ds_write_b128 v93, v[14:17]
	s_waitcnt vmcnt(3)
	ds_write_b128 v94, v[18:21]
	s_waitcnt vmcnt(2)
	ds_write_b128 v95, v[22:25]
	s_waitcnt vmcnt(1)
	ds_write_b128 v96, v[26:29]
	s_waitcnt vmcnt(0)
	ds_write_b128 v99, v[30:33]
	s_waitcnt lgkmcnt(0)
	s_barrier
	s_barrier
